# moba_attn: cnt kept in LDS and both list-row loads of a unit in flight together (2 fewer dependent global round trips per unit)
# baseline (speedup 1.0000x reference)
.LBB0_1233:
	s_cmp_ge_i32 s17, s94
	s_cselect_b64 s[2:3], -1, 0
	s_and_b64 s[0:1], s[2:3], s[0:1]
	v_writelane_b32 v255, s0, 6
	s_andn2_b64 vcc, exec, s[0:1]
	s_nop 0
	v_writelane_b32 v255, s1, 7
	s_cbranch_vccnz .LBB0_1362
	v_mov_b32_e32 v2, v211
	s_movk_i32 s0, 0x100
	s_nop 0
	v_cmp_gt_i32_e32 vcc, s0, v2
	s_and_saveexec_b64 s[0:1], vcc
	s_cbranch_execz .LBB0_1236
	v_readlane_b32 s2, v253, 15
	v_ashrrev_i32_e32 v3, 31, v2
	v_readlane_b32 s3, v253, 16
	s_waitcnt vmcnt(6)
	s_nop 0
	v_lshl_add_u64 v[4:5], v[2:3], 2, s[2:3]
	global_load_dword v0, v[4:5], off
	v_lshl_add_u32 v3, v2, 2, 0
	s_waitcnt vmcnt(0)
	v_lshlrev_b32_e32 v4, 1, v2
	ds_write_b16 v4, v0 offset:1032
	v_add_u32_e32 v0, 0xff, v0
	v_lshrrev_b32_e32 v0, 8, v0
	v_add_u32_e32 v0, 1, v0
	ds_write_b32 v3, v0 offset:4

.LBB0_1255:
	s_ashr_i32 s1, s0, 31
	s_lshl_b64 s[2:3], s[0:1], 2
	v_readlane_b32 s6, v253, 15
	v_readlane_b32 s7, v253, 16
	s_add_u32 s2, s6, s2
	s_addc_u32 s3, s7, s3
	s_lshl_b32 s2, s0, 1
	v_mov_b32_e32 v4, s2
	ds_read_u16 v4, v4 offset:1032
	s_cmp_eq_u32 s38, s4
	s_cselect_b64 s[42:43], -1, 0
	s_cmp_lg_u32 s38, s4
	s_cselect_b64 s[2:3], -1, 0
	s_not_b32 s4, s4
	s_add_i32 s4, s38, s4
	s_lshl_b32 s4, s4, 8
	s_lshl_b64 s[0:1], s[0:1], 13
	v_readlane_b32 s5, v253, 25
	s_add_u32 s0, s5, s0
	v_readlane_b32 s5, v253, 26
	s_addc_u32 s1, s5, s1
	s_mov_b64 s[6:7], -1
	s_and_b64 vcc, exec, s[2:3]
	s_cbranch_vccz .LBB0_1259
	v_add_u32_e32 v2, s4, v138
	s_waitcnt lgkmcnt(0)
	v_cmp_lt_i32_e32 vcc, v2, v4
	s_mov_b64 s[6:7], 0
	v_mov_b32_e32 v148, s19
	s_mov_b64 s[72:73], 0
	s_and_saveexec_b64 s[8:9], vcc
	s_cbranch_execz .LBB0_1258
	v_ashrrev_i32_e32 v3, 31, v2
	v_lshl_add_u64 v[2:3], v[2:3], 1, s[0:1]
	global_load_ushort v148, v[2:3], off
	s_mov_b64 s[72:73], exec

.LBB0_1260:
	s_waitcnt lgkmcnt(0)
	v_add_u32_e32 v148, s19, v138
	s_or_b64 s[72:73], s[72:73], exec
.LBB0_1261:
	s_andn2_b64 vcc, exec, s[2:3]
	s_mov_b64 s[6:7], -1
	s_cbranch_vccnz .LBB0_1265
	v_add_u32_e32 v2, s4, v153
	s_waitcnt lgkmcnt(0)
	v_cmp_lt_i32_e32 vcc, v2, v4
	s_mov_b64 s[6:7], 0
	v_mov_b32_e32 v146, s19
	s_mov_b64 s[40:41], 0
	s_and_saveexec_b64 s[8:9], vcc
	s_cbranch_execz .LBB0_1264
	s_ashr_i32 s5, s4, 31
	v_lshl_add_u64 v[2:3], s[4:5], 0, v[138:139]
	v_lshl_add_u64 v[2:3], v[2:3], 1, s[0:1]
	global_load_ushort v146, v[2:3], off offset:32
	s_mov_b64 s[40:41], exec

.LBB0_1266:
	s_waitcnt lgkmcnt(0)
	v_add_u32_e32 v146, s19, v153
	s_or_b64 s[40:41], s[40:41], exec
